# FFN-in unit loop: constant-stride next-tile indices on a 256-workgroup grid instead of the general index arithmetic
# baseline (speedup 1.0000x reference)
.LBB0_119:
	s_add_i32 s86, s86, 1
	s_cmpk_lg_i32 s70, 0x100
	s_cbranch_scc1 .Lffnin_next_general
	s_cmp_lt_u32 s86, 8
	s_cselect_b64 s[38:39], -1, 0
	s_mov_b32 s8, s21
	s_add_i32 s6, s20, 4
	s_branch .LBB0_125
.Lffnin_next_general:
	v_readlane_b32 s3, v251, 36
	s_mul_i32 s7, s86, s3
	s_mul_hi_u32 s9, s86, s70
	s_add_i32 s9, s9, s7
	s_mul_i32 s7, s86, s70
	s_add_u32 s40, s7, s72
	s_addc_u32 s41, s9, s73
	v_mov_b64_e32 v[2:3], 0x800
	v_cmp_lt_i64_e64 s[38:39], s[40:41], v[2:3]
	v_mov_b64_e32 v[2:3], 0x7ff
	v_cmp_gt_i64_e32 vcc, s[40:41], v[2:3]
	s_cbranch_vccnz .LBB0_125
	s_ashr_i32 s6, s40, 31
	s_lshr_b32 s6, s6, 29
	s_add_i32 s8, s40, s6
	s_and_b32 s6, s8, -8
	s_sub_i32 s9, s40, s6
	s_cmp_gt_i32 s9, -1
	s_mov_b64 s[6:7], -1
	s_cbranch_scc0 .LBB0_122
	s_lshl_b32 s13, s9, 8
	s_mov_b64 s[6:7], 0
